# P11 LN2 epilogue: H1F residual loads of batches 1-4 issued with batch 0 (own register sets), batch 5 after batch 0, on v17
# baseline (speedup 1.0000x reference)
.LBB0_1049:
	s_lshl_b32 s20, s24, 8
	s_add_i32 s1, s20, s35
	s_lshl_b32 s0, s11, 5
	v_or_b32_e32 v146, s1, v172
	s_lshl_b32 s1, s10, 8
	s_or_b32 s0, s1, s0
	v_and_or_b32 v128, v145, 12, s0
	v_ashrrev_i32_e32 v147, 31, v146
	v_ashrrev_i32_e32 v129, 31, v128
	v_lshlrev_b64 v[130:131], 12, v[146:147]
	v_lshl_add_u64 v[130:131], s[72:73], 0, v[130:131]
	v_lshlrev_b64 v[160:161], 2, v[128:129]
	v_lshl_add_u64 v[128:129], v[130:131], 0, v[160:161]
	s_barrier
	global_load_dwordx4 v[130:133], v[128:129], off nt
	global_load_dwordx4 v[134:137], v[128:129], off offset:64 nt
	global_load_dwordx4 v[138:141], v[128:129], off offset:512 nt
	global_load_dwordx4 v[142:145], v[128:129], off offset:576 nt
	s_mov_b64 s[28:29], 0x10000
	v_lshl_add_u64 v[240:241], v[128:129], 0, s[28:29]
	global_load_dwordx4 v[176:179], v[240:241], off nt
	global_load_dwordx4 v[180:183], v[240:241], off offset:64 nt
	global_load_dwordx4 v[184:187], v[240:241], off offset:512 nt
	global_load_dwordx4 v[188:191], v[240:241], off offset:576 nt
	s_mov_b64 s[28:29], 0x20000
	v_lshl_add_u64 v[240:241], v[128:129], 0, s[28:29]
	global_load_dwordx4 v[192:195], v[240:241], off nt
	global_load_dwordx4 v[196:199], v[240:241], off offset:64 nt
	global_load_dwordx4 v[200:203], v[240:241], off offset:512 nt
	global_load_dwordx4 v[204:207], v[240:241], off offset:576 nt
	s_mov_b64 s[28:29], 0x30000
	v_lshl_add_u64 v[240:241], v[128:129], 0, s[28:29]
	global_load_dwordx4 v[208:211], v[240:241], off nt
	global_load_dwordx4 v[212:215], v[240:241], off offset:64 nt
	global_load_dwordx4 v[216:219], v[240:241], off offset:512 nt
	global_load_dwordx4 v[220:223], v[240:241], off offset:576 nt
	s_mov_b64 s[28:29], 0x80000
	v_lshl_add_u64 v[240:241], v[128:129], 0, s[28:29]
	global_load_dwordx4 v[224:227], v[240:241], off nt
	global_load_dwordx4 v[228:231], v[240:241], off offset:64 nt
	global_load_dwordx4 v[232:235], v[240:241], off offset:512 nt
	global_load_dwordx4 v[236:239], v[240:241], off offset:576 nt
	v_or_b32_e32 v148, 16, v146
	v_ashrrev_i32_e32 v149, 31, v148
	v_lshlrev_b64 v[148:149], 12, v[148:149]
	s_mov_b32 s0, 0x3f9837f0
	v_lshl_add_u64 v[148:149], s[72:73], 0, v[148:149]
	v_lshl_add_u64 v[148:149], v[148:149], 0, v[160:161]
	s_mov_b64 s[2:3], 0x80000
	s_waitcnt vmcnt(16)
	v_pk_fma_f32 v[126:127], v[132:133], s[0:1], v[126:127] op_sel_hi:[1,0,1]
	v_pk_fma_f32 v[124:125], v[130:131], s[0:1], v[124:125] op_sel_hi:[1,0,1]
	v_pk_fma_f32 v[122:123], v[136:137], s[0:1], v[122:123] op_sel_hi:[1,0,1]
	v_pk_fma_f32 v[120:121], v[134:135], s[0:1], v[120:121] op_sel_hi:[1,0,1]
	v_pk_fma_f32 v[114:115], v[140:141], s[0:1], v[114:115] op_sel_hi:[1,0,1]
	v_pk_fma_f32 v[112:113], v[138:139], s[0:1], v[112:113] op_sel_hi:[1,0,1]
	v_pk_fma_f32 v[110:111], v[144:145], s[0:1], v[110:111] op_sel_hi:[1,0,1]
	v_pk_fma_f32 v[108:109], v[142:143], s[0:1], v[108:109] op_sel_hi:[1,0,1]
	s_nop 0
	s_mov_b64 s[28:29], 0x90000
	v_lshl_add_u64 v[240:241], v[128:129], 0, s[28:29]
	global_load_dwordx4 v[130:133], v[240:241], off nt
	global_load_dwordx4 v[134:137], v[240:241], off offset:64 nt
	global_load_dwordx4 v[138:141], v[240:241], off offset:512 nt
	global_load_dwordx4 v[142:145], v[240:241], off offset:576 nt
	v_or_b32_e32 v148, 32, v146
	v_ashrrev_i32_e32 v149, 31, v148
	v_lshlrev_b64 v[148:149], 12, v[148:149]
	v_lshl_add_u64 v[148:149], s[72:73], 0, v[148:149]
	v_lshl_add_u64 v[148:149], v[148:149], 0, v[160:161]
	v_or_b32_e32 v146, 48, v146
	v_ashrrev_i32_e32 v147, 31, v146
	v_lshlrev_b64 v[146:147], 12, v[146:147]
	v_lshl_add_u64 v[146:147], s[72:73], 0, v[146:147]
	v_lshl_add_u64 v[146:147], v[146:147], 0, v[160:161]
	v_mov_b32_e32 v150, v125
	v_mov_b32_e32 v151, v126
	v_mov_b32_e32 v152, v124
	v_mov_b32_e32 v153, v127
	v_mov_b32_e32 v154, v121
	v_mov_b32_e32 v155, v122
	v_pk_add_f32 v[150:151], v[150:151], v[152:153]
	v_add_f32_e32 v157, v114, v115
	v_add_f32_e32 v150, v150, v151
	v_mov_b32_e32 v156, v109
	v_mov_b32_e32 v158, v111
	v_add_f32_e32 v159, 0, v150
	s_waitcnt vmcnt(19)
	v_pk_fma_f32 v[118:119], v[178:179], s[0:1], v[118:119] op_sel_hi:[1,0,1]
	v_pk_fma_f32 v[116:117], v[176:177], s[0:1], v[116:117] op_sel_hi:[1,0,1]
	s_waitcnt vmcnt(18)
	v_pk_fma_f32 v[102:103], v[182:183], s[0:1], v[102:103] op_sel_hi:[1,0,1]
	v_pk_fma_f32 v[100:101], v[180:181], s[0:1], v[100:101] op_sel_hi:[1,0,1]
	s_waitcnt vmcnt(17)
	v_pk_fma_f32 v[90:91], v[186:187], s[0:1], v[90:91] op_sel_hi:[1,0,1]
	v_pk_fma_f32 v[88:89], v[184:185], s[0:1], v[88:89] op_sel_hi:[1,0,1]
	s_waitcnt vmcnt(16)
	v_pk_fma_f32 v[82:83], v[190:191], s[0:1], v[82:83] op_sel_hi:[1,0,1]
	v_pk_fma_f32 v[80:81], v[188:189], s[0:1], v[80:81] op_sel_hi:[1,0,1]
	s_nop 0
	s_waitcnt vmcnt(15)
	v_pk_fma_f32 v[106:107], v[194:195], s[0:1], v[106:107] op_sel_hi:[1,0,1]
	v_pk_fma_f32 v[104:105], v[192:193], s[0:1], v[104:105] op_sel_hi:[1,0,1]
	s_waitcnt vmcnt(14)
	v_pk_fma_f32 v[94:95], v[198:199], s[0:1], v[94:95] op_sel_hi:[1,0,1]
	v_pk_fma_f32 v[92:93], v[196:197], s[0:1], v[92:93] op_sel_hi:[1,0,1]
	s_waitcnt vmcnt(13)
	v_pk_fma_f32 v[86:87], v[202:203], s[0:1], v[86:87] op_sel_hi:[1,0,1]
	v_pk_fma_f32 v[84:85], v[200:201], s[0:1], v[84:85] op_sel_hi:[1,0,1]
	s_waitcnt vmcnt(12)
	v_pk_fma_f32 v[74:75], v[206:207], s[0:1], v[74:75] op_sel_hi:[1,0,1]
	v_pk_fma_f32 v[72:73], v[204:205], s[0:1], v[72:73] op_sel_hi:[1,0,1]
	s_mov_b32 s1, 0x80000
	v_add_co_u32_e32 v146, vcc, s1, v128
	s_waitcnt vmcnt(11)
	v_pk_fma_f32 v[98:99], v[210:211], s[0:1], v[98:99] op_sel_hi:[1,0,1]
	v_pk_fma_f32 v[96:97], v[208:209], s[0:1], v[96:97] op_sel_hi:[1,0,1]
	s_waitcnt vmcnt(10)
	v_pk_fma_f32 v[78:79], v[214:215], s[0:1], v[78:79] op_sel_hi:[1,0,1]
	v_pk_fma_f32 v[76:77], v[212:213], s[0:1], v[76:77] op_sel_hi:[1,0,1]
	s_waitcnt vmcnt(9)
	v_pk_fma_f32 v[70:71], v[218:219], s[0:1], v[70:71] op_sel_hi:[1,0,1]
	v_pk_fma_f32 v[68:69], v[216:217], s[0:1], v[68:69] op_sel_hi:[1,0,1]
	s_waitcnt vmcnt(8)
	v_pk_fma_f32 v[66:67], v[222:223], s[0:1], v[66:67] op_sel_hi:[1,0,1]
	v_pk_fma_f32 v[64:65], v[220:221], s[0:1], v[64:65] op_sel_hi:[1,0,1]
	v_addc_co_u32_e32 v147, vcc, 0, v129, vcc
	s_nop 0
	s_mov_b32 s1, 0x90000
	s_mov_b64 s[2:3], 0x90000
	v_add_co_u32_e32 v146, vcc, s1, v128
	s_waitcnt vmcnt(6)
	v_pk_fma_f32 v[58:59], v[230:231], s[0:1], v[58:59] op_sel_hi:[1,0,1]
	v_addc_co_u32_e32 v147, vcc, 0, v129, vcc
	v_pk_fma_f32 v[62:63], v[226:227], s[0:1], v[62:63] op_sel_hi:[1,0,1]
	v_pk_fma_f32 v[60:61], v[224:225], s[0:1], v[60:61] op_sel_hi:[1,0,1]
	v_pk_fma_f32 v[56:57], v[228:229], s[0:1], v[56:57] op_sel_hi:[1,0,1]
	s_waitcnt vmcnt(5)
	v_pk_fma_f32 v[54:55], v[234:235], s[0:1], v[54:55] op_sel_hi:[1,0,1]
	v_pk_fma_f32 v[52:53], v[232:233], s[0:1], v[52:53] op_sel_hi:[1,0,1]
	s_waitcnt vmcnt(4)
	v_pk_fma_f32 v[50:51], v[238:239], s[0:1], v[50:51] op_sel_hi:[1,0,1]
	v_pk_fma_f32 v[48:49], v[236:237], s[0:1], v[48:49] op_sel_hi:[1,0,1]
	s_nop 0
	s_mov_b32 s1, 0xa0000
	s_mov_b64 s[2:3], 0xa0000
	v_add_co_u32_e32 v146, vcc, s1, v128
	s_waitcnt vmcnt(2)
	v_pk_fma_f32 v[42:43], v[136:137], s[0:1], v[42:43] op_sel_hi:[1,0,1]
	v_pk_fma_f32 v[46:47], v[132:133], s[0:1], v[46:47] op_sel_hi:[1,0,1]
	v_pk_fma_f32 v[44:45], v[130:131], s[0:1], v[44:45] op_sel_hi:[1,0,1]
	v_pk_fma_f32 v[40:41], v[134:135], s[0:1], v[40:41] op_sel_hi:[1,0,1]
	s_waitcnt vmcnt(1)
	v_pk_fma_f32 v[38:39], v[140:141], s[0:1], v[38:39] op_sel_hi:[1,0,1]
	v_pk_fma_f32 v[36:37], v[138:139], s[0:1], v[36:37] op_sel_hi:[1,0,1]
	s_waitcnt vmcnt(0)
	v_pk_fma_f32 v[34:35], v[144:145], s[0:1], v[34:35] op_sel_hi:[1,0,1]
	v_pk_fma_f32 v[32:33], v[142:143], s[0:1], v[32:33] op_sel_hi:[1,0,1]
	v_addc_co_u32_e32 v147, vcc, 0, v129, vcc
	v_lshl_add_u64 v[130:131], v[128:129], 0, s[2:3]
	global_load_dwordx4 v[132:135], v[146:147], off nt
	global_load_dwordx4 v[136:139], v[130:131], off offset:64 nt
	global_load_dwordx4 v[140:143], v[130:131], off offset:512 nt
	s_nop 0
	global_load_dwordx4 v[144:147], v[130:131], off offset:576 nt
	v_mbcnt_lo_u32_b32 v130, -1, 0
	v_mbcnt_hi_u32_b32 v131, -1, v130
	v_and_b32_e32 v148, 64, v131
	v_xor_b32_e32 v130, 16, v131
	v_add_u32_e32 v163, 64, v148
	s_mov_b64 s[2:3], 0xb0000
	s_mov_b32 s1, 0xb0000
	v_cmp_lt_i32_e32 vcc, v130, v163
	v_lshl_add_u64 v[148:149], v[128:129], 0, s[2:3]
	s_waitcnt vmcnt(2)
	v_pk_fma_f32 v[26:27], v[138:139], s[0:1], v[26:27] op_sel_hi:[1,0,1]
	v_cndmask_b32_e32 v130, v131, v130, vcc
	v_add_co_u32_e32 v128, vcc, s1, v128
	v_pk_fma_f32 v[30:31], v[134:135], s[0:1], v[30:31] op_sel_hi:[1,0,1]
	s_nop 0
	v_addc_co_u32_e32 v129, vcc, 0, v129, vcc
	v_pk_fma_f32 v[28:29], v[132:133], s[0:1], v[28:29] op_sel_hi:[1,0,1]
	v_pk_fma_f32 v[24:25], v[136:137], s[0:1], v[24:25] op_sel_hi:[1,0,1]
	s_waitcnt vmcnt(1)
	v_pk_fma_f32 v[22:23], v[142:143], s[0:1], v[22:23] op_sel_hi:[1,0,1]
	v_pk_fma_f32 v[20:21], v[140:141], s[0:1], v[20:21] op_sel_hi:[1,0,1]
	s_waitcnt vmcnt(0)
	v_pk_fma_f32 v[18:19], v[146:147], s[0:1], v[18:19] op_sel_hi:[1,0,1]
	v_pk_fma_f32 v[16:17], v[144:145], s[0:1], v[16:17] op_sel_hi:[1,0,1]
	v_add_f32_e32 v133, v112, v113
	global_load_dwordx4 v[134:137], v[128:129], off nt
	global_load_dwordx4 v[138:141], v[148:149], off offset:64 nt
	global_load_dwordx4 v[142:145], v[148:149], off offset:512 nt
	v_mov_b32_e32 v128, v120
	global_load_dwordx4 v[146:149], v[148:149], off offset:576 nt
	v_mov_b32_e32 v129, v123
	v_pk_add_f32 v[128:129], v[154:155], v[128:129]
	v_mov_b32_e32 v132, v108
	v_pk_add_f32 v[128:129], v[128:129], v[128:129] op_sel_hi:[0,1]
	v_mov_b32_e32 v128, v110
	v_pk_add_f32 v[132:133], v[132:133], v[156:157]
	v_pk_add_f32 v[128:129], v[128:129], v[158:159]
	v_lshlrev_b32_e32 v130, 2, v130
	v_pk_add_f32 v[128:129], v[132:133], v[128:129]
	s_waitcnt vmcnt(3)
	v_pk_fma_f32 v[14:15], v[136:137], s[0:1], v[14:15] op_sel_hi:[1,0,1]
	v_add_f32_e32 v129, v128, v129
	ds_bpermute_b32 v132, v130, v129
	v_xor_b32_e32 v128, 32, v131
	v_cmp_lt_i32_e32 vcc, v128, v163
	v_pk_fma_f32 v[12:13], v[134:135], s[0:1], v[12:13] op_sel_hi:[1,0,1]
	s_waitcnt vmcnt(2)
	v_pk_fma_f32 v[10:11], v[140:141], s[0:1], v[10:11] op_sel_hi:[1,0,1]
	v_cndmask_b32_e32 v128, v131, v128, vcc
	v_lshlrev_b32_e32 v128, 2, v128
	s_waitcnt lgkmcnt(0)
	v_add_f32_e32 v129, v129, v132
	ds_bpermute_b32 v131, v128, v129
	v_pk_fma_f32 v[8:9], v[138:139], s[0:1], v[8:9] op_sel_hi:[1,0,1]
	s_waitcnt vmcnt(1)
	v_pk_fma_f32 v[6:7], v[144:145], s[0:1], v[6:7] op_sel_hi:[1,0,1]
	v_pk_fma_f32 v[4:5], v[142:143], s[0:1], v[4:5] op_sel_hi:[1,0,1]
	s_waitcnt vmcnt(0)
	v_pk_fma_f32 v[2:3], v[148:149], s[0:1], v[2:3] op_sel_hi:[1,0,1]
	s_waitcnt lgkmcnt(0)
	v_add_f32_e32 v131, v129, v131
	v_fmamk_f32 v132, v131, 0xbc800000, v127
	v_fmamk_f32 v150, v131, 0xbc800000, v125
	v_fmamk_f32 v152, v131, 0xbc800000, v123
	v_fmamk_f32 v154, v131, 0xbc800000, v121
	v_fmamk_f32 v129, v131, 0xbc800000, v126
	v_fmamk_f32 v133, v131, 0xbc800000, v124
	v_fmamk_f32 v151, v131, 0xbc800000, v122
	v_fmamk_f32 v153, v131, 0xbc800000, v120
	v_fmamk_f32 v156, v131, 0xbc800000, v115
	v_fmamk_f32 v158, v131, 0xbc800000, v113
	v_mul_f32_e32 v150, v150, v150
	v_mul_f32_e32 v132, v132, v132
	v_mul_f32_e32 v154, v154, v154
	v_mul_f32_e32 v152, v152, v152
	v_fmamk_f32 v155, v131, 0xbc800000, v114
	v_fmamk_f32 v157, v131, 0xbc800000, v112
	v_fmamk_f32 v163, v131, 0xbc800000, v111
	v_fmamk_f32 v165, v131, 0xbc800000, v109
	v_mul_f32_e32 v158, v158, v158
	v_mul_f32_e32 v156, v156, v156
	v_fmac_f32_e32 v150, v133, v133
	v_fmac_f32_e32 v132, v129, v129
	v_fmac_f32_e32 v154, v153, v153
	v_fmac_f32_e32 v152, v151, v151
	v_fmamk_f32 v159, v131, 0xbc800000, v110
	v_fmamk_f32 v164, v131, 0xbc800000, v108
	v_mul_f32_e32 v165, v165, v165
	v_mul_f32_e32 v163, v163, v163
	v_fmac_f32_e32 v158, v157, v157
	v_fmac_f32_e32 v156, v155, v155
	v_add_f32_e32 v129, v150, v132
	v_add_f32_e32 v132, v154, v152
	v_fmac_f32_e32 v165, v164, v164
	v_fmac_f32_e32 v163, v159, v159
	v_add_f32_e32 v133, v158, v156
	v_add_f32_e32 v129, v129, v132
	v_add_f32_e32 v150, v165, v163
	v_add_f32_e32 v129, v133, v129
	v_add_f32_e32 v132, v150, v129
	ds_bpermute_b32 v133, v130, v132
	v_pk_fma_f32 v[0:1], v[146:147], s[0:1], v[0:1] op_sel_hi:[1,0,1]
	s_lshl_b32 s0, s11, 3
	s_waitcnt lgkmcnt(0)
	v_add_f32_e32 v132, v132, v133
	ds_bpermute_b32 v133, v128, v132
	v_cmp_gt_u32_e32 vcc, 16, v170
	v_lshlrev_b32_e32 v129, 5, v172
	s_add_i32 s2, s0, 0
	s_and_saveexec_b64 s[0:1], vcc
	s_cbranch_execz .LBB0_1051
	s_lshl_b32 s3, s27, 11
	s_add_i32 s3, s2, s3
	v_mul_f32_e32 v134, 0x3c800000, v131
	v_add_u32_e32 v131, s3, v129
	s_waitcnt lgkmcnt(0)
	v_add_f32_e32 v135, v132, v133
	ds_write_b64 v131, v[134:135]
